# branch and out GEMM phases: workgroups start with a small XCD-dependent delay (s_sleep steps by XCC id) so the XCDs do not walk the same weight panels in lockstep
# speedup vs baseline: 1.0229x; 1.0229x over previous
; #define OPAQUE_V(x) asm volatile("" : "+v"(x))
; #define OPAQUE_S(x) asm volatile("" : "+s"(x))
; #define PG8_BAR __builtin_amdgcn_s_barrier()
; template <bool ALIGN_EPI, bool SP2, class Epi, class Sched>
; __device__ __forceinline__ void gemm_phase(LAS unsigned char* lds, const Gemm g, const Sched& S, const Epi& E) {
;     int tid_ = threadIdx.x; OPAQUE_V(tid_); int K_ = g.K; OPAQUE_S(K_);
;     const int tid = tid_, wid = __builtin_amdgcn_readfirstlane(tid >> 6), lane = tid & 63, wr = wid >> 2, wc = wid & 3, fr = lane & 15, fq = lane >> 4;
;     const int K = K_, nt = K / BK;
;     unsigned voffA[2], voffB[2];
; #pragma unroll
;     for (int i = 0; i < 2; ++i) { int R, C; stage_rc(tid * 16 + i * 8192, R, C); const int Rb = Epi::PERM ? ((R & ~31) + perm32(R & 31)) : R;
;         voffA[i] = (unsigned)(R * K + C) * 2u; voffB[i] = (unsigned)(Rb * K + C) * 2u; }
;     const size_t kstep = (size_t)(BK * 2);
;     const size_t hstep = (size_t)HALF * K * 2;
;     const size_t tstep = 2 * hstep;
;     const unsigned ldsw = (unsigned)wid * 1024u;
;     const int aoff = lds_byte(wr * 64 + fr, fq * 8), boff = lds_byte(wc * 32 + fr, fq * 8);
;     ...
;     Unit cur, nxt; int ui = 0;
;     if (!S.next(0, cur)) return;
;     f32x4 acc[2][2][4][2];
; #pragma unroll
;     for (int a = 0; a < 2; ++a)
; #pragma unroll
;         for (int b = 0; b < 2; ++b)
; #pragma unroll
;             for (int m = 0; m < 4; ++m)
; #pragma unroll
;                 for (int n = 0; n < 2; ++n) acc[a][b][m][n] = (f32x4){0.f, 0.f, 0.f, 0.f};
;     bf16x8 At[4][2], B0[2][2], B1[2][2];
;     const char* cA = (const char*)g.A + (size_t)cur.pm * tstep; const char* cB = (const char*)g.Bt + (size_t)cur.pn * tstep;
;     if constexpr (SP2) {
;         PG8_STAGE(PG8_SB(0, 0), cB, voffB); PG8_STAGE(PG8_SB(0, 1), cB + hstep, voffB); PG8_STAGE(PG8_SA(0, 0), cA, voffA); PG8_STAGE(PG8_SA(0, 1), cA + hstep, voffA);
;         if (wr == 1) PG8_BAR;
; __global__ void __launch_bounds__(512, 2) fwd_megakernel(Params p_unused) {
;     ...
;             pg8::Gemm g{(const bf16_t*)(ws + WS_Y), (const bf16_t*)(ws + WS_WB) + (size_t)l * 4 * 2048 * 1024, 4 * SEQ, 4 * 2048, 1024};
;             pg8::BrOrder S; S.so.init(SEQ, DM, gridDim.x, vc);
;             pg8::EpiBr E{(const bf16_t*)(ws + WS_HG), (bf16_t*)(ws + WS_MG)};
;             pg8::gemm_phase<GEMM_ALIGN, GEMM_SP2>(lds, g, S, E);
.LBB0_686:
	s_and_b64 vcc, exec, s[40:41]
	s_cbranch_vccnz .LBB0_760
	s_getreg_b32 s98, hwreg(HW_REG_XCC_ID, 0, 4)
	s_and_b32 s98, s98, 7
.Lskew_br:
	s_cmp_eq_u32 s98, 0
	s_cbranch_scc1 .Lskew_br_done
	s_sleep 12
	s_sub_i32 s98, s98, 1
	s_branch .Lskew_br
.Lskew_br_done:
	v_bfe_i32 v4, v0, 27, 1
	v_lshlrev_b32_e32 v2, 4, v0
	v_lshrrev_b32_e32 v4, 22, v4
	v_add_u32_e32 v4, v2, v4
	v_and_b32_e32 v4, 0xfffffc00, v4
	v_sub_u32_e32 v4, v2, v4
	v_ashrrev_i32_e32 v3, 31, v0
	v_lshrrev_b32_e32 v5, 4, v4
	v_lshrrev_b32_e32 v3, 26, v3
	v_bitop3_b32 v4, v5, v4, 32 bitop3:0x6c
	v_add_u32_e32 v3, v0, v3
	v_ashrrev_i32_e32 v6, 31, v4
	s_waitcnt lgkmcnt(0)
	s_add_u32 s6, s28, 0x30b00000
	v_readlane_b32 s14, v240, 33
	v_ashrrev_i32_e32 v3, 6, v3
	v_lshrrev_b32_e32 v6, 26, v6
	s_addc_u32 s22, s29, 0
	s_lshl_b32 s14, s14, 24
	v_lshlrev_b32_e32 v5, 3, v3
	v_add_u32_e32 v6, v4, v6
	v_readlane_b32 s15, v240, 34
	s_add_u32 s14, s28, s14
	v_and_b32_e32 v5, -16, v5
	v_ashrrev_i32_e32 v7, 6, v6
	v_lshlrev_b32_e32 v3, 5, v3
	s_addc_u32 s15, s29, 0
	v_add_u32_e32 v5, v7, v5
	v_and_b32_e32 v14, 32, v3
	v_and_b32_e32 v3, 0xc0, v6
	s_add_u32 s23, s14, 0x9200000
	v_sub_u32_e32 v3, v4, v3
	v_lshlrev_b32_e32 v4, 1, v5
	v_lshrrev_b32_e32 v6, 2, v5
	v_and_b32_e32 v7, 3, v7
	s_mov_b32 s14, 0x7fffffe0
	v_ashrrev_i16_sdwa v3, v168, sext(v3) dst_sel:DWORD dst_unused:UNUSED_PAD src0_sel:DWORD src1_sel:BYTE_0
	v_and_b32_e32 v4, 24, v4
	v_and_b32_e32 v6, 4, v6
	v_and_or_b32 v7, v5, s14, v7
	v_bfe_i32 v15, v3, 0, 16
	v_or3_b32 v4, v7, v6, v4
	v_add_u32_e32 v3, v14, v15
	v_mul_lo_u32 v16, v5, s42
	v_mul_lo_u32 v4, v4, s42
	v_add_u32_e32 v2, 0x2000, v2
	v_add_lshl_u32 v148, v3, v16, 1
	v_add_lshl_u32 v150, v4, v3, 1
	v_ashrrev_i32_e32 v3, 31, v2
	v_lshrrev_b32_e32 v3, 22, v3
	v_add_u32_e32 v3, v2, v3
	v_ashrrev_i32_e32 v3, 10, v3
	v_mul_i32_i24_e32 v4, 0x400, v3
	s_addc_u32 s25, s15, 0
	v_sub_u32_e32 v2, v2, v4
	s_ashr_i32 s43, s42, 31
	v_lshrrev_b32_e32 v4, 4, v2
	s_lshl_b64 s[26:27], s[42:43], 9
	s_ashr_i32 s34, s66, 31
	v_bitop3_b32 v2, v4, v2, 32 bitop3:0x6c
	s_mul_i32 s34, s26, s34
	s_mul_hi_u32 s35, s26, s66
	v_ashrrev_i32_e32 v5, 31, v2
	s_add_i32 s36, s35, s34
	s_lshr_b64 s[34:35], s[42:43], 23
	v_lshrrev_b32_e32 v5, 26, v5
	s_mul_i32 s35, s34, s66
	v_lshlrev_b32_e32 v4, 3, v3
	v_add_u32_e32 v5, v2, v5
	s_add_i32 s36, s36, s35
	s_ashr_i32 s35, s70, 31
	v_and_b32_e32 v4, -16, v4
	v_ashrrev_i32_e32 v6, 6, v5
	s_mul_i32 s35, s26, s35
	s_mul_hi_u32 s38, s26, s70
	s_ashr_i32 s44, s24, 6
	v_add_u32_e32 v4, v6, v4
	v_lshlrev_b32_e32 v3, 5, v3
	v_and_b32_e32 v6, 3, v6
	s_add_i32 s35, s38, s35
	s_mul_i32 s34, s34, s70
	v_and_b32_e32 v17, 32, v3
	v_and_b32_e32 v3, 0xc0, v5
	v_and_or_b32 v6, v4, s14, v6
	s_ashr_i32 s45, s24, 8
	s_lshl_b64 s[14:15], s[42:43], 8
	s_lshl_b32 s61, s44, 10
	s_add_i32 s35, s35, s34
	s_mul_i32 s34, s26, s70
	v_sub_u32_e32 v2, v2, v3
	v_lshlrev_b32_e32 v3, 1, v4
	v_lshrrev_b32_e32 v5, 2, v4
	s_add_u32 s92, s23, s34
	v_ashrrev_i16_sdwa v2, v168, sext(v2) dst_sel:DWORD dst_unused:UNUSED_PAD src0_sel:DWORD src1_sel:BYTE_0
	v_and_b32_e32 v3, 24, v3
	v_and_b32_e32 v5, 4, v5
	s_addc_u32 s93, s25, s35
	s_add_i32 s62, s61, 0
	v_bfe_i32 v18, v2, 0, 16
	v_or3_b32 v3, v6, v5, v3
	s_add_i32 m0, s62, 0x10000
	v_add_u32_e32 v2, v17, v18
	v_mul_lo_u32 v3, v3, s42
	global_load_lds_dwordx4 v150, s[92:93]
	s_add_i32 m0, s62, 0x12000
	v_add_lshl_u32 v154, v3, v2, 1
	s_add_u32 s34, s92, s14
	global_load_lds_dwordx4 v154, s[92:93]
	s_addc_u32 s35, s93, s15
	s_add_i32 m0, s62, 0x14000
	s_mul_i32 s37, s26, s66
	global_load_lds_dwordx4 v150, s[34:35]
	s_add_i32 m0, s62, 0x16000
	s_add_u32 s94, s6, s37
	v_mov_b32_e32 v151, v1
	v_mov_b32_e32 v155, v1
	s_addc_u32 s95, s22, s36
	s_add_i32 s63, s62, 0x2000
	v_mul_lo_u32 v19, v4, s42
	v_lshl_add_u64 v[6:7], s[34:35], 0, v[150:151]
	v_lshl_add_u64 v[8:9], s[34:35], 0, v[154:155]
	global_load_lds_dwordx4 v154, s[34:35]
	s_mov_b32 m0, s62
	s_add_u32 s34, s94, s14
	v_add_lshl_u32 v152, v2, v19, 1
	global_load_lds_dwordx4 v148, s[94:95]
	s_mov_b32 m0, s63
	s_addc_u32 s35, s95, s15
	s_add_i32 s64, s62, 0x4000
	global_load_lds_dwordx4 v152, s[94:95]
	s_mov_b32 m0, s64
	s_add_i32 s65, s62, 0x6000
	global_load_lds_dwordx4 v148, s[34:35]
	s_mov_b32 m0, s65
	v_mov_b32_e32 v149, v1
	global_load_lds_dwordx4 v152, s[34:35]
	v_mov_b32_e32 v153, v1
	s_cmp_eq_u32 s45, 1
	v_lshl_add_u64 v[2:3], s[92:93], 0, v[150:151]
	v_lshl_add_u64 v[4:5], s[92:93], 0, v[154:155]
	v_lshl_add_u64 v[10:11], s[94:95], 0, v[148:149]
	v_lshl_add_u64 v[12:13], s[94:95], 0, v[152:153]
	s_cselect_b64 s[34:35], -1, 0
	s_cmp_lg_u32 s45, 1
	s_cbranch_scc1 .LBB0_689
	s_barrier

; __global__ void __launch_bounds__(512, 2) fwd_megakernel(Params p_unused) {
;     ...
;         if (IN(pb + 4)) for (int rep_ = 0; rep_ < ((((REP_MASK >> 5) & 1u) && l == 0) ? 2 : 1); ++rep_) {
;             pg8::Gemm g{(const bf16_t*)(ws + WS_MG), (const bf16_t*)(ws + WS_WO) + (size_t)l * 2048 * 2048, SEQ, DM, DM};
;             pg8::StaticOrder S; S.init(SEQ, DM, gridDim.x, vc);
.LBB0_816:
	s_andn2_b64 vcc, exec, s[14:15]
	s_cbranch_vccnz .LBB0_896
	v_mov_b32_e32 v2, v166
	s_movk_i32 s42, 0x800
	s_and_b64 vcc, exec, s[40:41]
	v_readfirstlane_b32 s24, v2
	s_cbranch_vccnz .LBB0_842
	s_getreg_b32 s98, hwreg(HW_REG_XCC_ID, 0, 4)
	s_and_b32 s98, s98, 7

; #define OPAQUE_V(x) asm volatile("" : "+v"(x))
; #define OPAQUE_S(x) asm volatile("" : "+s"(x))
; #define PG8_BAR __builtin_amdgcn_s_barrier()
; template <bool ALIGN_EPI, bool SP2, class Epi, class Sched>
; __device__ __forceinline__ void gemm_phase(LAS unsigned char* lds, const Gemm g, const Sched& S, const Epi& E) {
;     int tid_ = threadIdx.x; OPAQUE_V(tid_); int K_ = g.K; OPAQUE_S(K_);
;     const int tid = tid_, wid = __builtin_amdgcn_readfirstlane(tid >> 6), lane = tid & 63, wr = wid >> 2, wc = wid & 3, fr = lane & 15, fq = lane >> 4;
;     const int K = K_, nt = K / BK;
;     unsigned voffA[2], voffB[2];
; #pragma unroll
;     for (int i = 0; i < 2; ++i) { int R, C; stage_rc(tid * 16 + i * 8192, R, C); const int Rb = Epi::PERM ? ((R & ~31) + perm32(R & 31)) : R;
;         voffA[i] = (unsigned)(R * K + C) * 2u; voffB[i] = (unsigned)(Rb * K + C) * 2u; }
;     const size_t kstep = (size_t)(BK * 2);
;     const size_t hstep = (size_t)HALF * K * 2;
;     const size_t tstep = 2 * hstep;
;     const unsigned ldsw = (unsigned)wid * 1024u;
;     const int aoff = lds_byte(wr * 64 + fr, fq * 8), boff = lds_byte(wc * 32 + fr, fq * 8);
;     ...
;     Unit cur, nxt; int ui = 0;
;     if (!S.next(0, cur)) return;
;     f32x4 acc[2][2][4][2];
; #pragma unroll
;     for (int a = 0; a < 2; ++a)
; #pragma unroll
;         for (int b = 0; b < 2; ++b)
; #pragma unroll
;             for (int m = 0; m < 4; ++m)
; #pragma unroll
;                 for (int n = 0; n < 2; ++n) acc[a][b][m][n] = (f32x4){0.f, 0.f, 0.f, 0.f};
;     bf16x8 At[4][2], B0[2][2], B1[2][2];
;     const char* cA = (const char*)g.A + (size_t)cur.pm * tstep; const char* cB = (const char*)g.Bt + (size_t)cur.pn * tstep;
;     if constexpr (SP2) {
;         PG8_STAGE(PG8_SB(0, 0), cB, voffB); PG8_STAGE(PG8_SB(0, 1), cB + hstep, voffB); PG8_STAGE(PG8_SA(0, 0), cA, voffA); PG8_STAGE(PG8_SA(0, 1), cA + hstep, voffA);
;         if (wr == 1) PG8_BAR;
; __global__ void __launch_bounds__(512, 2) fwd_megakernel(Params p_unused) {
;     ...
;             pg8::Gemm g{(const bf16_t*)(ws + WS_MG), (const bf16_t*)(ws + WS_WO) + (size_t)l * 2048 * 2048, SEQ, DM, DM};
;             pg8::StaticOrder S; S.init(SEQ, DM, gridDim.x, vc);
;             pg8::EpiOut E{l == 0 ? p->in[0] : (const float*)p->out, p->out};
;             pg8::gemm_phase<GEMM_ALIGN, GEMM_SP2>(lds, g, S, E);
.Lskew_out_done:
	v_lshlrev_b32_e32 v3, 4, v2
	v_add_u32_e32 v0, 0x2000, v3
	v_ashrrev_i32_e32 v4, 31, v0
	v_lshrrev_b32_e32 v4, 22, v4
	v_add_u32_e32 v4, v0, v4
	v_ashrrev_i32_e32 v4, 10, v4
	v_mul_i32_i24_e32 v5, 0x400, v4
	v_sub_u32_e32 v0, v0, v5
	v_lshrrev_b32_e32 v5, 4, v0
	v_bitop3_b32 v6, v5, v0, 32 bitop3:0x6c
	v_ashrrev_i32_e32 v0, 31, v6
	v_lshrrev_b32_e32 v0, 26, v0
	v_add_u32_e32 v7, v6, v0
	v_lshlrev_b32_e32 v5, 3, v4
	v_ashrrev_i32_e32 v0, 6, v7
	v_and_b32_e32 v5, 0x7ffffff0, v5
	v_add_u32_e32 v5, v0, v5
	v_lshlrev_b32_e32 v0, 5, v4
	v_and_b32_e32 v0, 32, v0
	v_mad_u64_u32 v[4:5], s[36:37], v5, s42, v[0:1]
	v_and_b32_e32 v0, 0xc0, v7
	v_sub_u32_e32 v0, v6, v0
	v_ashrrev_i16_sdwa v0, v168, sext(v0) dst_sel:DWORD dst_unused:UNUSED_PAD src0_sel:DWORD src1_sel:BYTE_0
	v_bfe_i32 v0, v0, 0, 16
	v_add_lshl_u32 v130, v4, v0, 1
	v_bfe_i32 v0, v2, 27, 1
	v_lshrrev_b32_e32 v0, 22, v0
	v_add_u32_e32 v0, v3, v0
	s_waitcnt lgkmcnt(0)
	s_add_u32 s6, s28, 0x18300000
	v_readlane_b32 s14, v240, 33
	v_and_b32_e32 v0, 0xfffffc00, v0
	s_addc_u32 s22, s29, 0
	s_lshl_b32 s14, s14, 23
	v_sub_u32_e32 v0, v3, v0
	v_readlane_b32 s15, v240, 34
	s_add_u32 s14, s28, s14
	v_lshrrev_b32_e32 v3, 4, v0
	v_ashrrev_i32_e32 v4, 31, v2
	s_addc_u32 s15, s29, 0
	v_bitop3_b32 v3, v3, v0, 32 bitop3:0x6c
	v_lshrrev_b32_e32 v4, 26, v4
	s_add_u32 s23, s14, 0xb200000
	v_ashrrev_i32_e32 v0, 31, v3
	v_add_u32_e32 v4, v2, v4
	s_addc_u32 s25, s15, 0
	v_readlane_b32 s14, v240, 17
	v_lshrrev_b32_e32 v0, 26, v0
	v_ashrrev_i32_e32 v4, 6, v4
	v_readlane_b32 s15, v240, 18
	v_add_u32_e32 v6, v3, v0
	v_lshlrev_b32_e32 v5, 3, v4
	s_and_b64 s[14:15], s[14:15], exec
	v_ashrrev_i32_e32 v0, 6, v6
	v_and_b32_e32 v5, 0x7ffffff0, v5
	s_cselect_b32 s14, 0, 0x90
	v_add_u32_e32 v5, v0, v5
	v_lshlrev_b32_e32 v0, 5, v4
	s_add_u32 s34, s0, s14
	v_and_b32_e32 v0, 32, v0
	s_addc_u32 s35, s1, 0
	s_ashr_i32 s43, s42, 31
	v_mad_u64_u32 v[4:5], s[36:37], v5, s42, v[0:1]
	s_lshl_b64 s[26:27], s[42:43], 9
	v_readlane_b32 s36, v240, 9
	v_readlane_b32 s39, v240, 8
	s_mul_i32 s36, s26, s36
	s_mul_hi_u32 s37, s26, s39
	s_add_i32 s38, s37, s36
	s_lshr_b64 s[36:37], s[42:43], 23
	s_mul_i32 s37, s36, s39
	s_add_i32 s38, s38, s37
	s_mul_i32 s37, s26, s39
	v_readlane_b32 s39, v240, 11
	v_readlane_b32 s41, v240, 10
	s_mul_i32 s39, s26, s39
	s_mul_hi_u32 s40, s26, s41
	s_ashr_i32 s44, s24, 6
	v_and_b32_e32 v0, 0xc0, v6
	s_add_i32 s39, s40, s39
	s_mul_i32 s36, s36, s41
	s_ashr_i32 s45, s24, 8
	s_lshl_b64 s[14:15], s[42:43], 8
	s_lshl_b32 s61, s44, 10
	v_sub_u32_e32 v0, v3, v0
	s_add_i32 s39, s39, s36
	s_mul_i32 s36, s26, s41
	v_ashrrev_i16_sdwa v0, v168, sext(v0) dst_sel:DWORD dst_unused:UNUSED_PAD src0_sel:DWORD src1_sel:BYTE_0
	s_add_u32 s90, s23, s36
	v_bfe_i32 v0, v0, 0, 16
	s_addc_u32 s91, s25, s39
	s_add_i32 s62, s61, 0
	v_add_lshl_u32 v0, v4, v0, 1
	s_add_i32 m0, s62, 0x10000
	s_nop 0
	global_load_lds_dwordx4 v0, s[90:91]
	s_add_i32 m0, s62, 0x12000
	s_add_u32 s40, s90, s14
	global_load_lds_dwordx4 v130, s[90:91]
	s_addc_u32 s41, s91, s15
	s_add_i32 m0, s62, 0x14000
	s_nop 0
	global_load_lds_dwordx4 v0, s[40:41]
	s_add_i32 m0, s62, 0x16000
	s_add_u32 s86, s6, s37
	s_addc_u32 s87, s22, s38
	s_add_i32 s63, s62, 0x2000
	global_load_lds_dwordx4 v130, s[40:41]
	s_mov_b32 m0, s62
	s_add_u32 s36, s86, s14
	global_load_lds_dwordx4 v0, s[86:87]
	s_mov_b32 m0, s63
	s_addc_u32 s37, s87, s15
	s_add_i32 s64, s62, 0x4000
	global_load_lds_dwordx4 v130, s[86:87]
	s_mov_b32 m0, s64
	s_add_i32 s65, s62, 0x6000
	global_load_lds_dwordx4 v0, s[36:37]
	s_mov_b32 m0, s65
	s_cmp_eq_u32 s45, 1
	global_load_lds_dwordx4 v130, s[36:37]
	s_load_dwordx2 s[34:35], s[34:35], 0x0
	s_nop 0
	s_load_dwordx2 s[36:37], s[0:1], 0x90
	s_cselect_b64 s[38:39], -1, 0
	s_cmp_lg_u32 s45, 1
	s_cbranch_scc1 .LBB0_820
	s_barrier

; __global__ void __launch_bounds__(512, 2) fwd_megakernel(Params p_unused) {
	.amdhsa_kernel _Z14fwd_megakernel6Params
		.amdhsa_group_segment_fixed_size 0
		.amdhsa_private_segment_fixed_size 0
		.amdhsa_kernarg_size 424
		.amdhsa_user_sgpr_count 2
		.amdhsa_user_sgpr_dispatch_ptr 0
		.amdhsa_user_sgpr_queue_ptr 0
		.amdhsa_user_sgpr_kernarg_segment_ptr 1
		.amdhsa_user_sgpr_dispatch_id 0
		.amdhsa_user_sgpr_kernarg_preload_length 0
		.amdhsa_user_sgpr_kernarg_preload_offset 0
		.amdhsa_user_sgpr_private_segment_size 0
		.amdhsa_uses_dynamic_stack 0
		.amdhsa_enable_private_segment 0
		.amdhsa_system_sgpr_workgroup_id_x 1
		.amdhsa_system_sgpr_workgroup_id_y 0
		.amdhsa_system_sgpr_workgroup_id_z 0
		.amdhsa_system_sgpr_workgroup_info 0
		.amdhsa_system_vgpr_workitem_id 2
		.amdhsa_next_free_vgpr 242
		.amdhsa_next_free_sgpr 100
		.amdhsa_accum_offset 244
		.amdhsa_reserve_vcc 1
		.amdhsa_float_round_mode_32 0
		.amdhsa_float_round_mode_16_64 0
		.amdhsa_float_denorm_mode_32 3
		.amdhsa_float_denorm_mode_16_64 3
		.amdhsa_dx10_clamp 1
		.amdhsa_ieee_mode 1
		.amdhsa_fp16_overflow 0
		.amdhsa_tg_split 0
		.amdhsa_exception_fp_ieee_invalid_op 0
		.amdhsa_exception_fp_denorm_src 0
		.amdhsa_exception_fp_ieee_div_zero 0
		.amdhsa_exception_fp_ieee_overflow 0
		.amdhsa_exception_fp_ieee_underflow 0
		.amdhsa_exception_fp_ieee_inexact 0
		.amdhsa_exception_int_div_zero 0
	.end_amdhsa_kernel

; __global__ void __launch_bounds__(512, 2) fwd_megakernel(Params p_unused) {
amdhsa.kernels:
  - .agpr_count:     0
    .args:
      - .offset:         0
        .size:           168
        .value_kind:     by_value
      - .offset:         168
        .size:           4
        .value_kind:     hidden_block_count_x
      - .offset:         172
        .size:           4
        .value_kind:     hidden_block_count_y
      - .offset:         176
        .size:           4
        .value_kind:     hidden_block_count_z
      - .offset:         180
        .size:           2
        .value_kind:     hidden_group_size_x
      - .offset:         182
        .size:           2
        .value_kind:     hidden_group_size_y
      - .offset:         184
        .size:           2
        .value_kind:     hidden_group_size_z
      - .offset:         186
        .size:           2
        .value_kind:     hidden_remainder_x
      - .offset:         188
        .size:           2
        .value_kind:     hidden_remainder_y
      - .offset:         190
        .size:           2
        .value_kind:     hidden_remainder_z
      - .offset:         208
        .size:           8
        .value_kind:     hidden_global_offset_x
      - .offset:         216
        .size:           8
        .value_kind:     hidden_global_offset_y
      - .offset:         224
        .size:           8
        .value_kind:     hidden_global_offset_z
      - .offset:         232
        .size:           2
        .value_kind:     hidden_grid_dims
      - .offset:         256
        .size:           8
        .value_kind:     hidden_multigrid_sync_arg
      - .offset:         288
        .size:           4
        .value_kind:     hidden_dynamic_lds_size
    .group_segment_fixed_size: 0
    .kernarg_segment_align: 8
    .kernarg_segment_size: 424
    .language:       OpenCL C
    .language_version:
      - 2
      - 0
    .max_flat_workgroup_size: 512
    .name:           _Z14fwd_megakernel6Params
    .private_segment_fixed_size: 0
    .sgpr_count:     106
    .sgpr_spill_count: 114
    .symbol:         _Z14fwd_megakernel6Params.kd
    .uniform_work_group_size: 1
    .uses_dynamic_stack: false
    .vgpr_count:     242
    .vgpr_spill_count: 0
    .wavefront_size: 64
